# rewritten up-GEMM epilogue + nt streaming stores on all GEMM epilogues + vmcnt(16) instead of vmcnt(0) before the partial-sum reduce
# baseline (speedup 1.0000x reference)
; #define PG8_LAS __attribute__((address_space(3)))
; __device__ __forceinline__ unsigned cvt_pk_bf16(float lo, float hi) { unsigned r; asm volatile("v_cvt_pk_bf16_f32 %0, %1, %2" : "=v"(r) : "v"(lo), "v"(hi)); return r; }
;     __device__ __forceinline__ void operator()(const f32x4 (&acc)[2][2][4][2], const Unit& u, int wr, int wc, int fr, int fq, PG8_LAS float* stash, int par, PG8_LAS unsigned char* stg, const Unit& un) const {
;     ...
;         float rsa[2][4];
; #pragma unroll
;         for (int ai = 0; ai < 2; ++ai)
; #pragma unroll
;             for (int m = 0; m < 4; ++m) rsa[ai][m] = stash[par * 256 + ai * HALF + wr * 64 + m * 16 + fr];
; #pragma unroll
;         for (int ai = 0; ai < 2; ++ai)
; #pragma unroll
;             for (int m = 0; m < 4; ++m) {
;                 const int row = u.pm * BM + ai * HALF + wr * 64 + m * 16 + fr;
;                 const float rs = rsa[ai][m];
;                 PG8_LAS unsigned char* st = stg + fr * 144 + fq * 16;
; #pragma unroll
;                 for (int bj = 0; bj < 2; ++bj) {
;                     float v[8];
; #pragma unroll
;                     for (int i = 0; i < 4; ++i) { v[i] = acc[ai][bj][m][0][i] * rs; v[4 + i] = acc[ai][bj][m][1][i] * rs; }
; #pragma unroll
;                     for (int i = 0; i < 8; ++i) { const float r = fmaxf(v[i], 0.f); v[i] = r * r; }
;                     u32x4 w; w.x = cvt_pk_bf16(v[0], v[1]); w.y = cvt_pk_bf16(v[2], v[3]); w.z = cvt_pk_bf16(v[4], v[5]); w.w = cvt_pk_bf16(v[6], v[7]);
;                     *(PG8_LAS u32x4*)(st + bj * 64) = w;
;                 }
; #pragma unroll
;                 for (int i = 0; i < 2; ++i) { const int c = fq * 16 + fr + 64 * i, rr = c >> 3, pc = c & 7;
;                     const u32x4 w = *(const PG8_LAS u32x4*)(stg + rr * 144 + pc * 16);
;                     __builtin_nontemporal_store(w, (u32x4*)(uo + (size_t)(row - fr + rr) * 4096 + u.pn * BM + wc * 64 + pc * 8)); }
;             }
.LBB0_848:
	v_lshl_add_u32 v144, v157, 10, v152
	ds_read2_b32 v[160:161], v144 offset1:16
	ds_read2_b32 v[148:149], v144 offset0:32 offset1:48
	ds_read2_b32 v[146:147], v144 offset0:128 offset1:144
	ds_read2_b32 v[144:145], v144 offset0:160 offset1:176
	s_lshl_b32 s16, s14, 8
	s_add_i32 s16, s16, s1
	s_lshl_b32 s100, s16, 13
	s_add_u32 s98, s78, s100
	s_addc_u32 s99, s79, 0
	s_lshl_b32 s100, s15, 9
	s_add_u32 s98, s98, s100
	s_addc_u32 s99, s99, 0
	s_add_u32 s98, s98, s74
	s_addc_u32 s99, s99, s75
	v_lshl_add_u32 v200, v153, 13, v0
	v_add_u32_e32 v201, 0x10000, v200
	s_waitcnt lgkmcnt(0)
	v_pk_mul_f32 v[126:127], v[126:127], v[160:161] op_sel_hi:[1,0]
	v_pk_mul_f32 v[128:129], v[128:129], v[160:161] op_sel_hi:[1,0]
	v_pk_mul_f32 v[122:123], v[122:123], v[160:161] op_sel_hi:[1,0]
	v_pk_mul_f32 v[124:125], v[124:125], v[160:161] op_sel_hi:[1,0]
	v_max_f32_e32 v126, 0, v126
	v_max_f32_e32 v127, 0, v127
	v_max_f32_e32 v128, 0, v128
	v_max_f32_e32 v129, 0, v129
	v_max_f32_e32 v122, 0, v122
	v_max_f32_e32 v123, 0, v123
	v_max_f32_e32 v124, 0, v124
	v_max_f32_e32 v125, 0, v125
	v_pk_mul_f32 v[126:127], v[126:127], v[126:127]
	v_pk_mul_f32 v[128:129], v[128:129], v[128:129]
	v_pk_mul_f32 v[122:123], v[122:123], v[122:123]
	v_pk_mul_f32 v[124:125], v[124:125], v[124:125]
	v_cvt_pk_bf16_f32 v126, v126, v127
	v_cvt_pk_bf16_f32 v127, v128, v129
	v_cvt_pk_bf16_f32 v128, v122, v123
	v_cvt_pk_bf16_f32 v129, v124, v125
	v_pk_mul_f32 v[118:119], v[118:119], v[160:161] op_sel_hi:[1,0]
	v_pk_mul_f32 v[120:121], v[120:121], v[160:161] op_sel_hi:[1,0]
	v_pk_mul_f32 v[114:115], v[114:115], v[160:161] op_sel_hi:[1,0]
	v_pk_mul_f32 v[116:117], v[116:117], v[160:161] op_sel_hi:[1,0]
	v_max_f32_e32 v118, 0, v118
	v_max_f32_e32 v119, 0, v119
	v_max_f32_e32 v120, 0, v120
	v_max_f32_e32 v121, 0, v121
	v_max_f32_e32 v114, 0, v114
	v_max_f32_e32 v115, 0, v115
	v_max_f32_e32 v116, 0, v116
	v_max_f32_e32 v117, 0, v117
	v_pk_mul_f32 v[118:119], v[118:119], v[118:119]
	v_pk_mul_f32 v[120:121], v[120:121], v[120:121]
	v_pk_mul_f32 v[114:115], v[114:115], v[114:115]
	v_pk_mul_f32 v[116:117], v[116:117], v[116:117]
	v_cvt_pk_bf16_f32 v118, v118, v119
	v_cvt_pk_bf16_f32 v119, v120, v121
	v_cvt_pk_bf16_f32 v120, v114, v115
	v_cvt_pk_bf16_f32 v121, v116, v117
	ds_write_b128 v156, v[126:129]
	ds_write_b128 v156, v[118:121] offset:64
	ds_read_b128 v[204:207], v158
	ds_read_b128 v[208:211], v158 offset:1152
	v_pk_mul_f32 v[110:111], v[110:111], v[160:161] op_sel:[0,1]
	v_pk_mul_f32 v[112:113], v[112:113], v[160:161] op_sel:[0,1]
	v_pk_mul_f32 v[106:107], v[106:107], v[160:161] op_sel:[0,1]
	v_pk_mul_f32 v[108:109], v[108:109], v[160:161] op_sel:[0,1]
	v_max_f32_e32 v110, 0, v110
	v_max_f32_e32 v111, 0, v111
	v_max_f32_e32 v112, 0, v112
	v_max_f32_e32 v113, 0, v113
	v_max_f32_e32 v106, 0, v106
	v_max_f32_e32 v107, 0, v107
	v_max_f32_e32 v108, 0, v108
	v_max_f32_e32 v109, 0, v109
	v_pk_mul_f32 v[110:111], v[110:111], v[110:111]
	v_pk_mul_f32 v[112:113], v[112:113], v[112:113]
	v_pk_mul_f32 v[106:107], v[106:107], v[106:107]
	v_pk_mul_f32 v[108:109], v[108:109], v[108:109]
	v_cvt_pk_bf16_f32 v110, v110, v111
	v_cvt_pk_bf16_f32 v111, v112, v113
	v_cvt_pk_bf16_f32 v112, v106, v107
	v_cvt_pk_bf16_f32 v113, v108, v109
	v_pk_mul_f32 v[102:103], v[102:103], v[160:161] op_sel:[0,1]
	v_pk_mul_f32 v[104:105], v[104:105], v[160:161] op_sel:[0,1]
	v_pk_mul_f32 v[98:99], v[98:99], v[160:161] op_sel:[0,1]
	v_pk_mul_f32 v[100:101], v[100:101], v[160:161] op_sel:[0,1]
	v_max_f32_e32 v102, 0, v102
	v_max_f32_e32 v103, 0, v103
	v_max_f32_e32 v104, 0, v104
	v_max_f32_e32 v105, 0, v105
	v_max_f32_e32 v98, 0, v98
	v_max_f32_e32 v99, 0, v99
	v_max_f32_e32 v100, 0, v100
	v_max_f32_e32 v101, 0, v101
	v_pk_mul_f32 v[102:103], v[102:103], v[102:103]
	v_pk_mul_f32 v[104:105], v[104:105], v[104:105]
	v_pk_mul_f32 v[98:99], v[98:99], v[98:99]
	v_pk_mul_f32 v[100:101], v[100:101], v[100:101]
	v_cvt_pk_bf16_f32 v102, v102, v103
	v_cvt_pk_bf16_f32 v103, v104, v105
	v_cvt_pk_bf16_f32 v104, v98, v99
	v_cvt_pk_bf16_f32 v105, v100, v101
	s_waitcnt lgkmcnt(0)
	global_store_dwordx4 v200, v[204:207], s[98:99] nt
	global_store_dwordx4 v201, v[208:211], s[98:99] nt
	ds_write_b128 v156, v[110:113]
	ds_write_b128 v156, v[102:105] offset:64
	ds_read_b128 v[212:215], v158
	ds_read_b128 v[216:219], v158 offset:1152
	v_pk_mul_f32 v[94:95], v[94:95], v[148:149] op_sel_hi:[1,0]
	v_pk_mul_f32 v[96:97], v[96:97], v[148:149] op_sel_hi:[1,0]
	v_pk_mul_f32 v[90:91], v[90:91], v[148:149] op_sel_hi:[1,0]
	v_pk_mul_f32 v[92:93], v[92:93], v[148:149] op_sel_hi:[1,0]
	v_max_f32_e32 v94, 0, v94
	v_max_f32_e32 v95, 0, v95
	v_max_f32_e32 v96, 0, v96
	v_max_f32_e32 v97, 0, v97
	v_max_f32_e32 v90, 0, v90
	v_max_f32_e32 v91, 0, v91
	v_max_f32_e32 v92, 0, v92
	v_max_f32_e32 v93, 0, v93
	v_pk_mul_f32 v[94:95], v[94:95], v[94:95]
	v_pk_mul_f32 v[96:97], v[96:97], v[96:97]
	v_pk_mul_f32 v[90:91], v[90:91], v[90:91]
	v_pk_mul_f32 v[92:93], v[92:93], v[92:93]
	v_cvt_pk_bf16_f32 v94, v94, v95
	v_cvt_pk_bf16_f32 v95, v96, v97
	v_cvt_pk_bf16_f32 v96, v90, v91
	v_cvt_pk_bf16_f32 v97, v92, v93
	v_pk_mul_f32 v[86:87], v[86:87], v[148:149] op_sel_hi:[1,0]
	v_pk_mul_f32 v[88:89], v[88:89], v[148:149] op_sel_hi:[1,0]
	v_pk_mul_f32 v[82:83], v[82:83], v[148:149] op_sel_hi:[1,0]
	v_pk_mul_f32 v[84:85], v[84:85], v[148:149] op_sel_hi:[1,0]
	v_max_f32_e32 v86, 0, v86
	v_max_f32_e32 v87, 0, v87
	v_max_f32_e32 v88, 0, v88
	v_max_f32_e32 v89, 0, v89
	v_max_f32_e32 v82, 0, v82
	v_max_f32_e32 v83, 0, v83
	v_max_f32_e32 v84, 0, v84
	v_max_f32_e32 v85, 0, v85
	v_pk_mul_f32 v[86:87], v[86:87], v[86:87]
	v_pk_mul_f32 v[88:89], v[88:89], v[88:89]
	v_pk_mul_f32 v[82:83], v[82:83], v[82:83]
	v_pk_mul_f32 v[84:85], v[84:85], v[84:85]
	v_cvt_pk_bf16_f32 v86, v86, v87
	v_cvt_pk_bf16_f32 v87, v88, v89
	v_cvt_pk_bf16_f32 v88, v82, v83
	v_cvt_pk_bf16_f32 v89, v84, v85
	s_waitcnt lgkmcnt(0)
; #define PG8_LAS __attribute__((address_space(3)))
; __device__ __forceinline__ unsigned cvt_pk_bf16(float lo, float hi) { unsigned r; asm volatile("v_cvt_pk_bf16_f32 %0, %1, %2" : "=v"(r) : "v"(lo), "v"(hi)); return r; }
;     __device__ __forceinline__ void operator()(const f32x4 (&acc)[2][2][4][2], const Unit& u, int wr, int wc, int fr, int fq, PG8_LAS float* stash, int par, PG8_LAS unsigned char* stg, const Unit& un) const {
;     ...
;         for (int ai = 0; ai < 2; ++ai)
; #pragma unroll
;             for (int m = 0; m < 4; ++m) {
;                 const int row = u.pm * BM + ai * HALF + wr * 64 + m * 16 + fr;
;                 const float rs = rsa[ai][m];
;                 PG8_LAS unsigned char* st = stg + fr * 144 + fq * 16;
; #pragma unroll
;                 for (int bj = 0; bj < 2; ++bj) {
;                     float v[8];
; #pragma unroll
;                     for (int i = 0; i < 4; ++i) { v[i] = acc[ai][bj][m][0][i] * rs; v[4 + i] = acc[ai][bj][m][1][i] * rs; }
; #pragma unroll
;                     for (int i = 0; i < 8; ++i) { const float r = fmaxf(v[i], 0.f); v[i] = r * r; }
;                     u32x4 w; w.x = cvt_pk_bf16(v[0], v[1]); w.y = cvt_pk_bf16(v[2], v[3]); w.z = cvt_pk_bf16(v[4], v[5]); w.w = cvt_pk_bf16(v[6], v[7]);
;                     *(PG8_LAS u32x4*)(st + bj * 64) = w;
;                 }
; #pragma unroll
;                 for (int i = 0; i < 2; ++i) { const int c = fq * 16 + fr + 64 * i, rr = c >> 3, pc = c & 7;
;                     const u32x4 w = *(const PG8_LAS u32x4*)(stg + rr * 144 + pc * 16);
;                     __builtin_nontemporal_store(w, (u32x4*)(uo + (size_t)(row - fr + rr) * 4096 + u.pn * BM + wc * 64 + pc * 8)); }
;             }
	s_add_u32 s100, s98, 0x20000
	s_addc_u32 s101, s99, 0
	global_store_dwordx4 v200, v[212:215], s[100:101] nt
	global_store_dwordx4 v201, v[216:219], s[100:101] nt
	ds_write_b128 v156, v[94:97]
	ds_write_b128 v156, v[86:89] offset:64
	ds_read_b128 v[204:207], v158
	ds_read_b128 v[208:211], v158 offset:1152
	v_pk_mul_f32 v[78:79], v[78:79], v[148:149] op_sel:[0,1]
	v_pk_mul_f32 v[80:81], v[80:81], v[148:149] op_sel:[0,1]
	v_pk_mul_f32 v[74:75], v[74:75], v[148:149] op_sel:[0,1]
	v_pk_mul_f32 v[76:77], v[76:77], v[148:149] op_sel:[0,1]
	v_max_f32_e32 v78, 0, v78
	v_max_f32_e32 v79, 0, v79
	v_max_f32_e32 v80, 0, v80
	v_max_f32_e32 v81, 0, v81
	v_max_f32_e32 v74, 0, v74
	v_max_f32_e32 v75, 0, v75
	v_max_f32_e32 v76, 0, v76
	v_max_f32_e32 v77, 0, v77
	v_pk_mul_f32 v[78:79], v[78:79], v[78:79]
	v_pk_mul_f32 v[80:81], v[80:81], v[80:81]
	v_pk_mul_f32 v[74:75], v[74:75], v[74:75]
	v_pk_mul_f32 v[76:77], v[76:77], v[76:77]
	v_cvt_pk_bf16_f32 v78, v78, v79
	v_cvt_pk_bf16_f32 v79, v80, v81
	v_cvt_pk_bf16_f32 v80, v74, v75
	v_cvt_pk_bf16_f32 v81, v76, v77
	v_pk_mul_f32 v[70:71], v[70:71], v[148:149] op_sel:[0,1]
	v_pk_mul_f32 v[72:73], v[72:73], v[148:149] op_sel:[0,1]
	v_pk_mul_f32 v[66:67], v[66:67], v[148:149] op_sel:[0,1]
	v_pk_mul_f32 v[68:69], v[68:69], v[148:149] op_sel:[0,1]
	v_max_f32_e32 v70, 0, v70
	v_max_f32_e32 v71, 0, v71
	v_max_f32_e32 v72, 0, v72
	v_max_f32_e32 v73, 0, v73
	v_max_f32_e32 v66, 0, v66
	v_max_f32_e32 v67, 0, v67
	v_max_f32_e32 v68, 0, v68
	v_max_f32_e32 v69, 0, v69
	v_pk_mul_f32 v[70:71], v[70:71], v[70:71]
	v_pk_mul_f32 v[72:73], v[72:73], v[72:73]
	v_pk_mul_f32 v[66:67], v[66:67], v[66:67]
	v_pk_mul_f32 v[68:69], v[68:69], v[68:69]
	v_cvt_pk_bf16_f32 v70, v70, v71
	v_cvt_pk_bf16_f32 v71, v72, v73
	v_cvt_pk_bf16_f32 v72, v66, v67
	v_cvt_pk_bf16_f32 v73, v68, v69
	s_waitcnt lgkmcnt(0)
	s_add_u32 s100, s98, 0x40000
	s_addc_u32 s101, s99, 0
	global_store_dwordx4 v200, v[204:207], s[100:101] nt
	global_store_dwordx4 v201, v[208:211], s[100:101] nt
	ds_write_b128 v156, v[78:81]
	ds_write_b128 v156, v[70:73] offset:64
	ds_read_b128 v[212:215], v158
	ds_read_b128 v[216:219], v158 offset:1152
	v_pk_mul_f32 v[62:63], v[62:63], v[146:147] op_sel_hi:[1,0]
	v_pk_mul_f32 v[64:65], v[64:65], v[146:147] op_sel_hi:[1,0]
	v_pk_mul_f32 v[58:59], v[58:59], v[146:147] op_sel_hi:[1,0]
	v_pk_mul_f32 v[60:61], v[60:61], v[146:147] op_sel_hi:[1,0]
	v_max_f32_e32 v62, 0, v62
	v_max_f32_e32 v63, 0, v63
	v_max_f32_e32 v64, 0, v64
	v_max_f32_e32 v65, 0, v65
	v_max_f32_e32 v58, 0, v58
	v_max_f32_e32 v59, 0, v59
	v_max_f32_e32 v60, 0, v60
	v_max_f32_e32 v61, 0, v61
	v_pk_mul_f32 v[62:63], v[62:63], v[62:63]
	v_pk_mul_f32 v[64:65], v[64:65], v[64:65]
	v_pk_mul_f32 v[58:59], v[58:59], v[58:59]
	v_pk_mul_f32 v[60:61], v[60:61], v[60:61]
	v_cvt_pk_bf16_f32 v62, v62, v63
	v_cvt_pk_bf16_f32 v63, v64, v65
	v_cvt_pk_bf16_f32 v64, v58, v59
	v_cvt_pk_bf16_f32 v65, v60, v61
	v_pk_mul_f32 v[54:55], v[54:55], v[146:147] op_sel_hi:[1,0]
	v_pk_mul_f32 v[56:57], v[56:57], v[146:147] op_sel_hi:[1,0]
	v_pk_mul_f32 v[50:51], v[50:51], v[146:147] op_sel_hi:[1,0]
	v_pk_mul_f32 v[52:53], v[52:53], v[146:147] op_sel_hi:[1,0]
	v_max_f32_e32 v54, 0, v54
	v_max_f32_e32 v55, 0, v55
	v_max_f32_e32 v56, 0, v56
	v_max_f32_e32 v57, 0, v57
	v_max_f32_e32 v50, 0, v50
	v_max_f32_e32 v51, 0, v51
	v_max_f32_e32 v52, 0, v52
	v_max_f32_e32 v53, 0, v53
	v_pk_mul_f32 v[54:55], v[54:55], v[54:55]
	v_pk_mul_f32 v[56:57], v[56:57], v[56:57]
	v_pk_mul_f32 v[50:51], v[50:51], v[50:51]
	v_pk_mul_f32 v[52:53], v[52:53], v[52:53]
	v_cvt_pk_bf16_f32 v54, v54, v55
	v_cvt_pk_bf16_f32 v55, v56, v57
	v_cvt_pk_bf16_f32 v56, v50, v51
	v_cvt_pk_bf16_f32 v57, v52, v53
	s_waitcnt lgkmcnt(0)
	s_add_u32 s100, s98, 0x60000
	s_addc_u32 s101, s99, 0
	global_store_dwordx4 v200, v[212:215], s[100:101] nt
	global_store_dwordx4 v201, v[216:219], s[100:101] nt
	ds_write_b128 v156, v[62:65]
	ds_write_b128 v156, v[54:57] offset:64
	ds_read_b128 v[204:207], v158
	ds_read_b128 v[208:211], v158 offset:1152
	v_pk_mul_f32 v[46:47], v[46:47], v[146:147] op_sel:[0,1]
	v_pk_mul_f32 v[48:49], v[48:49], v[146:147] op_sel:[0,1]
	v_pk_mul_f32 v[42:43], v[42:43], v[146:147] op_sel:[0,1]
	v_pk_mul_f32 v[44:45], v[44:45], v[146:147] op_sel:[0,1]
	v_max_f32_e32 v46, 0, v46
	v_max_f32_e32 v47, 0, v47
	v_max_f32_e32 v48, 0, v48
	v_max_f32_e32 v49, 0, v49
	v_max_f32_e32 v42, 0, v42
	v_max_f32_e32 v43, 0, v43
	v_max_f32_e32 v44, 0, v44
	v_max_f32_e32 v45, 0, v45
	v_pk_mul_f32 v[46:47], v[46:47], v[46:47]
	v_pk_mul_f32 v[48:49], v[48:49], v[48:49]
	v_pk_mul_f32 v[42:43], v[42:43], v[42:43]
	v_pk_mul_f32 v[44:45], v[44:45], v[44:45]
	v_cvt_pk_bf16_f32 v46, v46, v47
	v_cvt_pk_bf16_f32 v47, v48, v49
	v_cvt_pk_bf16_f32 v48, v42, v43
	v_cvt_pk_bf16_f32 v49, v44, v45
	v_pk_mul_f32 v[38:39], v[38:39], v[146:147] op_sel:[0,1]
	v_pk_mul_f32 v[40:41], v[40:41], v[146:147] op_sel:[0,1]
	v_pk_mul_f32 v[34:35], v[34:35], v[146:147] op_sel:[0,1]
	v_pk_mul_f32 v[36:37], v[36:37], v[146:147] op_sel:[0,1]
	v_max_f32_e32 v38, 0, v38
	v_max_f32_e32 v39, 0, v39
	v_max_f32_e32 v40, 0, v40
	v_max_f32_e32 v41, 0, v41
	v_max_f32_e32 v34, 0, v34
	v_max_f32_e32 v35, 0, v35
	v_max_f32_e32 v36, 0, v36
	v_max_f32_e32 v37, 0, v37
	v_pk_mul_f32 v[38:39], v[38:39], v[38:39]
	v_pk_mul_f32 v[40:41], v[40:41], v[40:41]
	v_pk_mul_f32 v[34:35], v[34:35], v[34:35]
	v_pk_mul_f32 v[36:37], v[36:37], v[36:37]
	v_cvt_pk_bf16_f32 v38, v38, v39
	v_cvt_pk_bf16_f32 v39, v40, v41
	v_cvt_pk_bf16_f32 v40, v34, v35
	v_cvt_pk_bf16_f32 v41, v36, v37
	s_waitcnt lgkmcnt(0)
; #define PG8_LAS __attribute__((address_space(3)))
; __device__ __forceinline__ unsigned cvt_pk_bf16(float lo, float hi) { unsigned r; asm volatile("v_cvt_pk_bf16_f32 %0, %1, %2" : "=v"(r) : "v"(lo), "v"(hi)); return r; }
;     __device__ __forceinline__ void operator()(const f32x4 (&acc)[2][2][4][2], const Unit& u, int wr, int wc, int fr, int fq, PG8_LAS float* stash, int par, PG8_LAS unsigned char* stg, const Unit& un) const {
;     ...
;         for (int ai = 0; ai < 2; ++ai)
; #pragma unroll
;             for (int m = 0; m < 4; ++m) {
;                 const int row = u.pm * BM + ai * HALF + wr * 64 + m * 16 + fr;
;                 const float rs = rsa[ai][m];
;                 PG8_LAS unsigned char* st = stg + fr * 144 + fq * 16;
; #pragma unroll
;                 for (int bj = 0; bj < 2; ++bj) {
;                     float v[8];
; #pragma unroll
;                     for (int i = 0; i < 4; ++i) { v[i] = acc[ai][bj][m][0][i] * rs; v[4 + i] = acc[ai][bj][m][1][i] * rs; }
; #pragma unroll
;                     for (int i = 0; i < 8; ++i) { const float r = fmaxf(v[i], 0.f); v[i] = r * r; }
;                     u32x4 w; w.x = cvt_pk_bf16(v[0], v[1]); w.y = cvt_pk_bf16(v[2], v[3]); w.z = cvt_pk_bf16(v[4], v[5]); w.w = cvt_pk_bf16(v[6], v[7]);
;                     *(PG8_LAS u32x4*)(st + bj * 64) = w;
;                 }
; #pragma unroll
;                 for (int i = 0; i < 2; ++i) { const int c = fq * 16 + fr + 64 * i, rr = c >> 3, pc = c & 7;
;                     const u32x4 w = *(const PG8_LAS u32x4*)(stg + rr * 144 + pc * 16);
;                     __builtin_nontemporal_store(w, (u32x4*)(uo + (size_t)(row - fr + rr) * 4096 + u.pn * BM + wc * 64 + pc * 8)); }
;             }
	s_add_u32 s100, s98, 0x100000
	s_addc_u32 s101, s99, 0
	global_store_dwordx4 v200, v[204:207], s[100:101] nt
	global_store_dwordx4 v201, v[208:211], s[100:101] nt
	ds_write_b128 v156, v[46:49]
	ds_write_b128 v156, v[38:41] offset:64
	ds_read_b128 v[212:215], v158
	ds_read_b128 v[216:219], v158 offset:1152
	v_pk_mul_f32 v[30:31], v[30:31], v[144:145] op_sel_hi:[1,0]
	v_pk_mul_f32 v[32:33], v[32:33], v[144:145] op_sel_hi:[1,0]
	v_pk_mul_f32 v[26:27], v[26:27], v[144:145] op_sel_hi:[1,0]
	v_pk_mul_f32 v[28:29], v[28:29], v[144:145] op_sel_hi:[1,0]
	v_max_f32_e32 v30, 0, v30
	v_max_f32_e32 v31, 0, v31
	v_max_f32_e32 v32, 0, v32
	v_max_f32_e32 v33, 0, v33
	v_max_f32_e32 v26, 0, v26
	v_max_f32_e32 v27, 0, v27
	v_max_f32_e32 v28, 0, v28
	v_max_f32_e32 v29, 0, v29
	v_pk_mul_f32 v[30:31], v[30:31], v[30:31]
	v_pk_mul_f32 v[32:33], v[32:33], v[32:33]
	v_pk_mul_f32 v[26:27], v[26:27], v[26:27]
	v_pk_mul_f32 v[28:29], v[28:29], v[28:29]
	v_cvt_pk_bf16_f32 v30, v30, v31
	v_cvt_pk_bf16_f32 v31, v32, v33
	v_cvt_pk_bf16_f32 v32, v26, v27
	v_cvt_pk_bf16_f32 v33, v28, v29
	v_pk_mul_f32 v[22:23], v[22:23], v[144:145] op_sel_hi:[1,0]
	v_pk_mul_f32 v[24:25], v[24:25], v[144:145] op_sel_hi:[1,0]
	v_pk_mul_f32 v[18:19], v[18:19], v[144:145] op_sel_hi:[1,0]
	v_pk_mul_f32 v[20:21], v[20:21], v[144:145] op_sel_hi:[1,0]
	v_max_f32_e32 v22, 0, v22
	v_max_f32_e32 v23, 0, v23
	v_max_f32_e32 v24, 0, v24
	v_max_f32_e32 v25, 0, v25
	v_max_f32_e32 v18, 0, v18
	v_max_f32_e32 v19, 0, v19
	v_max_f32_e32 v20, 0, v20
	v_max_f32_e32 v21, 0, v21
	v_pk_mul_f32 v[22:23], v[22:23], v[22:23]
	v_pk_mul_f32 v[24:25], v[24:25], v[24:25]
	v_pk_mul_f32 v[18:19], v[18:19], v[18:19]
	v_pk_mul_f32 v[20:21], v[20:21], v[20:21]
	v_cvt_pk_bf16_f32 v22, v22, v23
	v_cvt_pk_bf16_f32 v23, v24, v25
	v_cvt_pk_bf16_f32 v24, v18, v19
	v_cvt_pk_bf16_f32 v25, v20, v21
	s_waitcnt lgkmcnt(0)
	s_add_u32 s100, s98, 0x120000
	s_addc_u32 s101, s99, 0
	global_store_dwordx4 v200, v[212:215], s[100:101] nt
	global_store_dwordx4 v201, v[216:219], s[100:101] nt
	ds_write_b128 v156, v[30:33]
	ds_write_b128 v156, v[22:25] offset:64
	ds_read_b128 v[204:207], v158
	ds_read_b128 v[208:211], v158 offset:1152
	v_pk_mul_f32 v[14:15], v[14:15], v[144:145] op_sel:[0,1]
	v_pk_mul_f32 v[16:17], v[16:17], v[144:145] op_sel:[0,1]
	v_pk_mul_f32 v[10:11], v[10:11], v[144:145] op_sel:[0,1]
	v_pk_mul_f32 v[12:13], v[12:13], v[144:145] op_sel:[0,1]
	v_max_f32_e32 v14, 0, v14
	v_max_f32_e32 v15, 0, v15
	v_max_f32_e32 v16, 0, v16
	v_max_f32_e32 v17, 0, v17
	v_max_f32_e32 v10, 0, v10
	v_max_f32_e32 v11, 0, v11
	v_max_f32_e32 v12, 0, v12
	v_max_f32_e32 v13, 0, v13
	v_pk_mul_f32 v[14:15], v[14:15], v[14:15]
	v_pk_mul_f32 v[16:17], v[16:17], v[16:17]
	v_pk_mul_f32 v[10:11], v[10:11], v[10:11]
	v_pk_mul_f32 v[12:13], v[12:13], v[12:13]
	v_cvt_pk_bf16_f32 v14, v14, v15
	v_cvt_pk_bf16_f32 v15, v16, v17
	v_cvt_pk_bf16_f32 v16, v10, v11
	v_cvt_pk_bf16_f32 v17, v12, v13
	v_pk_mul_f32 v[6:7], v[6:7], v[144:145] op_sel:[0,1]
	v_pk_mul_f32 v[8:9], v[8:9], v[144:145] op_sel:[0,1]
	v_pk_mul_f32 v[2:3], v[2:3], v[144:145] op_sel:[0,1]
	v_pk_mul_f32 v[4:5], v[4:5], v[144:145] op_sel:[0,1]
	v_max_f32_e32 v6, 0, v6
	v_max_f32_e32 v7, 0, v7
	v_max_f32_e32 v8, 0, v8
	v_max_f32_e32 v9, 0, v9
	v_max_f32_e32 v2, 0, v2
	v_max_f32_e32 v3, 0, v3
	v_max_f32_e32 v4, 0, v4
	v_max_f32_e32 v5, 0, v5
	v_pk_mul_f32 v[6:7], v[6:7], v[6:7]
	v_pk_mul_f32 v[8:9], v[8:9], v[8:9]
	v_pk_mul_f32 v[2:3], v[2:3], v[2:3]
	v_pk_mul_f32 v[4:5], v[4:5], v[4:5]
	v_cvt_pk_bf16_f32 v6, v6, v7
	v_cvt_pk_bf16_f32 v7, v8, v9
	v_cvt_pk_bf16_f32 v8, v2, v3
	v_cvt_pk_bf16_f32 v9, v4, v5
	s_waitcnt lgkmcnt(0)
	s_add_u32 s100, s98, 0x140000
	s_addc_u32 s101, s99, 0
	global_store_dwordx4 v200, v[204:207], s[100:101] nt
	global_store_dwordx4 v201, v[208:211], s[100:101] nt
	ds_write_b128 v156, v[14:17]
	ds_write_b128 v156, v[6:9] offset:64
	ds_read_b128 v[212:215], v158
	ds_read_b128 v[216:219], v158 offset:1152
	s_waitcnt lgkmcnt(0)
	s_add_u32 s100, s98, 0x160000
	s_addc_u32 s101, s99, 0
	global_store_dwordx4 v200, v[212:215], s[100:101] nt
	global_store_dwordx4 v201, v[216:219], s[100:101] nt
	s_andn2_b64 vcc, exec, s[42:43]
	s_cbranch_vccnz .LBB0_852
; __device__ __forceinline__ float sum_x16(float s) { auto r = __builtin_amdgcn_permlane16_swap(__float_as_uint(s), __float_as_uint(s), false, false); return __uint_as_float(r[0]) + __uint_as_float(r[1]); }
; __device__ __forceinline__ float sum_x32(float s) { auto r = __builtin_amdgcn_permlane32_swap(__float_as_uint(s), __float_as_uint(s), false, false); return __uint_as_float(r[0]) + __uint_as_float(r[1]); }
; __device__ __forceinline__ void rows_part_reduce(const f32x4 (&pl)[2][4], float (&rs)[2][4]) {
; #pragma unroll
;     for (int ai = 0; ai < 2; ++ai)
; #pragma unroll
;         for (int m = 0; m < 4; ++m) { float s = (pl[ai][m][0] + pl[ai][m][1]) + (pl[ai][m][2] + pl[ai][m][3]); s = sum_x16(s); s = sum_x32(s); rs[ai][m] = __builtin_amdgcn_rsqf(s * (1.0f / 1024.0f) + 1e-6f); }
; }
;     __device__ __forceinline__ void operator()(const f32x4 (&acc)[2][2][4][2], const Unit& u, int wr, int wc, int fr, int fq, PG8_LAS float* stash, int par, PG8_LAS unsigned char* stg, const Unit& un) const {
;     ...
;         if (newpm) { float rsn[2][4]; rows_part_reduce(pln, rsn);
;           if (fq == 0) {
; #pragma unroll
;               for (int ai = 0; ai < 2; ++ai)
; #pragma unroll
;                   for (int m = 0; m < 4; ++m) stash[(par ^ 1) * 256 + ai * HALF + wr * 64 + m * 16 + fr] = rsn[ai][m]; } }
	s_waitcnt vmcnt(16)
	v_add_f32_e32 v2, v188, v195
	v_add_f32_e32 v3, v197, v198
	v_add_f32_e32 v4, v184, v192
	v_add_f32_e32 v5, v194, v196
	v_add_f32_e32 v6, v181, v189
	v_add_f32_e32 v7, v191, v193
	v_add_f32_e32 v8, v178, v185
	v_add_f32_e32 v9, v187, v190
	v_add_f32_e32 v10, v175, v180
	v_add_f32_e32 v11, v183, v186
	v_add_f32_e32 v12, v171, v176
	v_add_f32_e32 v13, v179, v182
	v_add_f32_e32 v14, v169, v172
	v_add_f32_e32 v15, v174, v177
	v_add_f32_e32 v16, v159, v168
	v_add_f32_e32 v17, v170, v173
	v_add_f32_e32 v2, v2, v3
	v_add_f32_e32 v4, v4, v5
	v_add_f32_e32 v6, v6, v7
	v_add_f32_e32 v8, v8, v9
	v_add_f32_e32 v10, v10, v11
	v_add_f32_e32 v12, v12, v13
	v_add_f32_e32 v14, v14, v15
	v_add_f32_e32 v16, v16, v17
	v_mov_b32_e32 v3, v2
	v_mov_b32_e32 v5, v4
	v_mov_b32_e32 v7, v6
	v_mov_b32_e32 v9, v8
	v_mov_b32_e32 v11, v10
	v_mov_b32_e32 v13, v12
	v_mov_b32_e32 v15, v14
	v_mov_b32_e32 v17, v16
	v_permlane16_swap_b32_e32 v2, v3
	v_permlane16_swap_b32_e32 v4, v5
	v_permlane16_swap_b32_e32 v6, v7
	v_permlane16_swap_b32_e32 v8, v9
	v_permlane16_swap_b32_e32 v10, v11
	v_permlane16_swap_b32_e32 v12, v13
	v_permlane16_swap_b32_e32 v14, v15
	v_permlane16_swap_b32_e32 v16, v17
	v_add_f32_e32 v2, v2, v3
	v_add_f32_e32 v4, v4, v5
	v_add_f32_e32 v6, v6, v7
	v_add_f32_e32 v8, v8, v9
	v_add_f32_e32 v10, v10, v11
	v_add_f32_e32 v12, v12, v13
	v_add_f32_e32 v14, v14, v15
	v_add_f32_e32 v16, v16, v17
	v_mov_b32_e32 v3, v2
	v_mov_b32_e32 v5, v4
	v_mov_b32_e32 v7, v6
	v_mov_b32_e32 v9, v8
	v_mov_b32_e32 v11, v10
	v_mov_b32_e32 v13, v12
	v_mov_b32_e32 v15, v14
	v_mov_b32_e32 v17, v16
	v_permlane32_swap_b32_e32 v2, v3
	v_permlane32_swap_b32_e32 v4, v5
	v_permlane32_swap_b32_e32 v6, v7
	v_permlane32_swap_b32_e32 v8, v9
	v_permlane32_swap_b32_e32 v10, v11
	v_permlane32_swap_b32_e32 v12, v13
	v_permlane32_swap_b32_e32 v14, v15
	v_permlane32_swap_b32_e32 v16, v17
	s_and_saveexec_b64 s[42:43], s[34:35]
	s_cbranch_execz .LBB0_851
	v_add_f32_e32 v16, v16, v17
	v_mov_b32_e32 v17, 0x358637bd
	v_add_f32_e32 v4, v4, v5
	v_add_f32_e32 v2, v2, v3
	v_add_f32_e32 v8, v8, v9
	v_add_f32_e32 v6, v6, v7
	v_fmamk_f32 v4, v4, 0x3a800000, v17
	v_fmamk_f32 v2, v2, 0x3a800000, v17
	v_add_f32_e32 v12, v12, v13
	v_add_f32_e32 v10, v10, v11
	v_fmamk_f32 v8, v8, 0x3a800000, v17
	v_fmamk_f32 v6, v6, 0x3a800000, v17
	v_rsq_f32_e32 v4, v4
	v_rsq_f32_e32 v2, v2
	v_add_f32_e32 v14, v14, v15
	v_fmamk_f32 v12, v12, 0x3a800000, v17
	v_fmamk_f32 v10, v10, 0x3a800000, v17
	v_rsq_f32_e32 v8, v8
	v_rsq_f32_e32 v6, v6
	v_lshlrev_b32_e32 v3, 10, v157
	v_fmamk_f32 v16, v16, 0x3a800000, v17
	v_fmamk_f32 v14, v14, 0x3a800000, v17
	v_rsq_f32_e32 v12, v12
	v_rsq_f32_e32 v10, v10
	v_xor_b32_e32 v3, 0x400, v3
	v_rsq_f32_e32 v16, v16
	v_rsq_f32_e32 v14, v14
	v_add_u32_e32 v3, v152, v3
	ds_write2_b32 v3, v2, v4 offset1:16
	ds_write2_b32 v3, v6, v8 offset0:32 offset1:48
	ds_write2_b32 v3, v10, v12 offset0:128 offset1:144
	ds_write2_b32 v3, v14, v16 offset0:160 offset1:176
